# static s_setprio 1 for waves 4-7 in the scan / SEL / OWN phases (younger-half priority raise), reset to 0 at every phase start
# baseline (speedup 1.0000x reference)
.LBB0_13:
	s_mov_b64 s[92:93], s[80:81]
	s_load_dwordx2 s[90:91], s[92:93], 0xb0
	s_setprio 0
	s_mov_b32 s0, 0x30050
	s_bitcmp1_b32 s0, s86
	s_cbranch_scc0 .Lprio_done
	v_readfirstlane_b32 s0, v156
	s_nop 3
	s_cmpk_lt_u32 s0, 0x100
	s_cbranch_scc1 .Lprio_done
	s_setprio 1
.Lprio_done:
	s_mov_b64 s[6:7], -1
	s_mov_b64 s[12:13], 0
	s_mov_b64 s[10:11], 0
	s_mov_b64 s[76:77], 0
	s_waitcnt lgkmcnt(0)
	s_add_u32 s94, s90, 0x4b00000
	s_addc_u32 s95, s91, 0
	s_add_u32 s96, s90, 0x2900000
	s_addc_u32 s97, s91, 0
	s_cmp_lt_i32 s86, 10
	s_mov_b64 s[28:29], 0
	s_cbranch_scc1 .LBB0_26
	s_cmp_gt_i32 s86, 14
	s_cbranch_scc0 .LBB0_80
	s_cmp_gt_i32 s86, 16
	s_cbranch_scc0 .LBB0_81
	s_cmp_gt_i32 s86, 17
	s_cbranch_scc0 .LBB0_23
	s_mov_b64 s[22:23], 0
	s_cmp_gt_i32 s86, 19
	s_cbranch_scc0 .LBB0_19
	s_mov_b64 s[6:7], 0
	s_mov_b64 s[28:29], -1
